# pre_phase adaLN GEMV k-loop unrolled x2 with double-buffered weight-row loads (next iteration in flight), on top of pipelined norm loops
# baseline (speedup 1.0000x reference)
.LBB0_33:
	s_mul_hi_i32 s2, s10, 0x2aaaaaab
	s_lshr_b32 s3, s2, 31
	s_ashr_i32 s2, s2, 3
	s_add_i32 s8, s2, s3
	s_mul_i32 s2, s8, 48
	s_sub_i32 s6, s10, s2
	s_mov_b64 s[2:3], s[0:1]
	s_load_dwordx2 s[4:5], s[2:3], 0xc0
	s_lshl_b32 s2, s6, 7
	s_ashr_i32 s3, s2, 31
	s_mul_i32 s7, s8, 0x1800000
	s_mul_hi_i32 s6, s8, 0x1800000
	s_waitcnt lgkmcnt(0)
	v_lshl_add_u64 v[0:1], s[4:5], 0, v[26:27]
	s_lshl_b64 s[4:5], s[2:3], 2
	s_add_u32 s4, s7, s4
	s_addc_u32 s5, s6, s5
	v_lshl_add_u64 v[28:29], v[0:1], 0, s[4:5]
	s_mov_b64 s[6:7], 0
	v_mov_b32_e32 v32, v30
	v_mov_b32_e32 v16, 0
	v_mov_b32_e32 v17, v23
	v_mov_b32_e32 v18, 0
	v_mov_b32_e32 v19, v23
	v_mov_b32_e32 v12, 0
	v_mov_b32_e32 v13, v23
	v_mov_b32_e32 v14, 0
	v_mov_b32_e32 v15, v23
	v_mov_b32_e32 v8, 0
	v_mov_b32_e32 v9, v23
	v_mov_b32_e32 v10, 0
	v_mov_b32_e32 v11, v23
	v_mov_b32_e32 v4, 0
	v_mov_b32_e32 v5, v23
	v_mov_b32_e32 v6, 0
	v_mov_b32_e32 v7, v23
	v_mov_b32_e32 v0, 0
	v_mov_b32_e32 v1, v23
	v_mov_b32_e32 v2, 0
	v_mov_b32_e32 v3, v23
	v_lshl_add_u64 v[146:147], v[28:29], 0, s[6:7]
	v_add_co_u32_e64 v148, s[4:5], s11, v146
	s_nop 1
	v_addc_co_u32_e64 v149, s[4:5], 0, v147, s[4:5]
	v_add_co_u32_e64 v150, s[4:5], s12, v146
	s_nop 1
	v_addc_co_u32_e64 v151, s[4:5], 0, v147, s[4:5]
	v_add_co_u32_e64 v152, s[4:5], s13, v146
	s_nop 1
	v_addc_co_u32_e64 v153, s[4:5], 0, v147, s[4:5]
	global_load_dwordx4 v[34:37], v[146:147], off
	global_load_dwordx4 v[38:41], v[148:149], off
	global_load_dwordx4 v[42:45], v[150:151], off
	global_load_dwordx4 v[46:49], v[152:153], off
	s_add_u32 s6, s6, 0x18000
	s_addc_u32 s7, s7, 0
.LBB0_34:
	v_lshl_add_u64 v[146:147], v[28:29], 0, s[6:7]
	v_add_co_u32_e64 v148, s[4:5], s11, v146
	s_nop 1
	v_addc_co_u32_e64 v149, s[4:5], 0, v147, s[4:5]
	v_add_co_u32_e64 v150, s[4:5], s12, v146
	s_nop 1
	v_addc_co_u32_e64 v151, s[4:5], 0, v147, s[4:5]
	v_add_co_u32_e64 v152, s[4:5], s13, v146
	s_nop 1
	v_addc_co_u32_e64 v153, s[4:5], 0, v147, s[4:5]
	global_load_dwordx4 v[130:133], v[146:147], off
	global_load_dwordx4 v[134:137], v[148:149], off
	global_load_dwordx4 v[138:141], v[150:151], off
	global_load_dwordx4 v[142:145], v[152:153], off
	s_add_u32 s6, s6, 0x18000
	s_addc_u32 s7, s7, 0
	ds_read_b128 v[50:53], v32
	ds_read_b128 v[54:57], v32 offset:4096
	ds_read_b128 v[58:61], v32 offset:8192
	ds_read_b128 v[62:65], v32 offset:12288
	ds_read_b128 v[66:69], v32 offset:16384
	s_waitcnt lgkmcnt(4)
	v_mov_b32_e32 v70, v53
	s_waitcnt lgkmcnt(3)
	v_mov_b32_e32 v72, v57
	s_waitcnt lgkmcnt(2)
	v_mov_b32_e32 v74, v61
	s_waitcnt lgkmcnt(1)
	v_mov_b32_e32 v76, v65
	s_waitcnt lgkmcnt(0)
	v_mov_b32_e32 v78, v69
	v_add_u32_e32 v32, 16, v32
	s_waitcnt vmcnt(7)
	v_pk_fma_f32 v[16:17], v[50:51], v[34:35], v[16:17] op_sel_hi:[0,1,1]
	v_pk_fma_f32 v[18:19], v[50:51], v[36:37], v[18:19] op_sel_hi:[0,1,1]
	v_pk_fma_f32 v[12:13], v[34:35], v[54:55], v[12:13] op_sel_hi:[1,0,1]
	v_pk_fma_f32 v[14:15], v[36:37], v[54:55], v[14:15] op_sel_hi:[1,0,1]
	v_pk_fma_f32 v[8:9], v[34:35], v[58:59], v[8:9] op_sel_hi:[1,0,1]
	v_pk_fma_f32 v[10:11], v[36:37], v[58:59], v[10:11] op_sel_hi:[1,0,1]
	v_pk_fma_f32 v[4:5], v[34:35], v[62:63], v[4:5] op_sel_hi:[1,0,1]
	v_pk_fma_f32 v[6:7], v[36:37], v[62:63], v[6:7] op_sel_hi:[1,0,1]
	v_pk_fma_f32 v[0:1], v[34:35], v[66:67], v[0:1] op_sel_hi:[1,0,1]
	v_pk_fma_f32 v[2:3], v[36:37], v[66:67], v[2:3] op_sel_hi:[1,0,1]
	s_waitcnt vmcnt(6)
	v_pk_fma_f32 v[16:17], v[50:51], v[38:39], v[16:17] op_sel:[1,0,0]
	v_pk_fma_f32 v[18:19], v[50:51], v[40:41], v[18:19] op_sel:[1,0,0]
	v_pk_fma_f32 v[12:13], v[38:39], v[54:55], v[12:13] op_sel:[0,1,0]
	v_pk_fma_f32 v[14:15], v[40:41], v[54:55], v[14:15] op_sel:[0,1,0]
	v_pk_fma_f32 v[8:9], v[38:39], v[58:59], v[8:9] op_sel:[0,1,0]
	v_pk_fma_f32 v[10:11], v[40:41], v[58:59], v[10:11] op_sel:[0,1,0]
	v_pk_fma_f32 v[4:5], v[38:39], v[62:63], v[4:5] op_sel:[0,1,0]
	v_pk_fma_f32 v[6:7], v[40:41], v[62:63], v[6:7] op_sel:[0,1,0]
	v_pk_fma_f32 v[0:1], v[38:39], v[66:67], v[0:1] op_sel:[0,1,0]
	v_pk_fma_f32 v[2:3], v[40:41], v[66:67], v[2:3] op_sel:[0,1,0]
	s_waitcnt vmcnt(5)
	v_pk_fma_f32 v[16:17], v[52:53], v[42:43], v[16:17] op_sel_hi:[0,1,1]
	v_pk_fma_f32 v[18:19], v[52:53], v[44:45], v[18:19] op_sel_hi:[0,1,1]
	v_pk_fma_f32 v[12:13], v[42:43], v[56:57], v[12:13] op_sel_hi:[1,0,1]
	v_pk_fma_f32 v[14:15], v[44:45], v[56:57], v[14:15] op_sel_hi:[1,0,1]
	v_pk_fma_f32 v[8:9], v[42:43], v[60:61], v[8:9] op_sel_hi:[1,0,1]
	v_pk_fma_f32 v[10:11], v[44:45], v[60:61], v[10:11] op_sel_hi:[1,0,1]
	v_pk_fma_f32 v[4:5], v[42:43], v[64:65], v[4:5] op_sel_hi:[1,0,1]
	v_pk_fma_f32 v[6:7], v[44:45], v[64:65], v[6:7] op_sel_hi:[1,0,1]
	v_pk_fma_f32 v[0:1], v[42:43], v[68:69], v[0:1] op_sel_hi:[1,0,1]
	v_pk_fma_f32 v[2:3], v[44:45], v[68:69], v[2:3] op_sel_hi:[1,0,1]
	s_waitcnt vmcnt(4)
	v_pk_fma_f32 v[16:17], v[70:71], v[46:47], v[16:17] op_sel_hi:[0,1,1]
	v_pk_fma_f32 v[18:19], v[70:71], v[48:49], v[18:19] op_sel_hi:[0,1,1]
	v_pk_fma_f32 v[12:13], v[46:47], v[72:73], v[12:13] op_sel_hi:[1,0,1]
	v_pk_fma_f32 v[14:15], v[48:49], v[72:73], v[14:15] op_sel_hi:[1,0,1]
	v_pk_fma_f32 v[8:9], v[46:47], v[74:75], v[8:9] op_sel_hi:[1,0,1]
	v_pk_fma_f32 v[10:11], v[48:49], v[74:75], v[10:11] op_sel_hi:[1,0,1]
	v_pk_fma_f32 v[4:5], v[46:47], v[76:77], v[4:5] op_sel_hi:[1,0,1]
	v_pk_fma_f32 v[6:7], v[48:49], v[76:77], v[6:7] op_sel_hi:[1,0,1]
	v_pk_fma_f32 v[0:1], v[46:47], v[78:79], v[0:1] op_sel_hi:[1,0,1]
	v_pk_fma_f32 v[2:3], v[48:49], v[78:79], v[2:3] op_sel_hi:[1,0,1]
	s_min_u32 s100, s6, 0x2e8000
	s_mov_b32 s101, 0
	v_lshl_add_u64 v[146:147], v[28:29], 0, s[100:101]
	v_add_co_u32_e64 v148, s[4:5], s11, v146
	s_nop 1
	v_addc_co_u32_e64 v149, s[4:5], 0, v147, s[4:5]
	v_add_co_u32_e64 v150, s[4:5], s12, v146
	s_nop 1
	v_addc_co_u32_e64 v151, s[4:5], 0, v147, s[4:5]
	v_add_co_u32_e64 v152, s[4:5], s13, v146
	s_nop 1
	v_addc_co_u32_e64 v153, s[4:5], 0, v147, s[4:5]
	global_load_dwordx4 v[34:37], v[146:147], off
	global_load_dwordx4 v[38:41], v[148:149], off
	global_load_dwordx4 v[42:45], v[150:151], off
	global_load_dwordx4 v[46:49], v[152:153], off
	s_add_u32 s6, s6, 0x18000
	s_addc_u32 s7, s7, 0
	ds_read_b128 v[50:53], v32
	ds_read_b128 v[54:57], v32 offset:4096
	ds_read_b128 v[58:61], v32 offset:8192
	ds_read_b128 v[62:65], v32 offset:12288
	ds_read_b128 v[66:69], v32 offset:16384
	s_waitcnt lgkmcnt(4)
	v_mov_b32_e32 v70, v53
	s_waitcnt lgkmcnt(3)
	v_mov_b32_e32 v72, v57
	s_waitcnt lgkmcnt(2)
	v_mov_b32_e32 v74, v61
	s_waitcnt lgkmcnt(1)
	v_mov_b32_e32 v76, v65
	s_waitcnt lgkmcnt(0)
	v_mov_b32_e32 v78, v69
	v_add_u32_e32 v32, 16, v32
	s_waitcnt vmcnt(7)
	v_pk_fma_f32 v[16:17], v[50:51], v[130:131], v[16:17] op_sel_hi:[0,1,1]
	v_pk_fma_f32 v[18:19], v[50:51], v[132:133], v[18:19] op_sel_hi:[0,1,1]
	v_pk_fma_f32 v[12:13], v[130:131], v[54:55], v[12:13] op_sel_hi:[1,0,1]
	v_pk_fma_f32 v[14:15], v[132:133], v[54:55], v[14:15] op_sel_hi:[1,0,1]
	v_pk_fma_f32 v[8:9], v[130:131], v[58:59], v[8:9] op_sel_hi:[1,0,1]
	v_pk_fma_f32 v[10:11], v[132:133], v[58:59], v[10:11] op_sel_hi:[1,0,1]
	v_pk_fma_f32 v[4:5], v[130:131], v[62:63], v[4:5] op_sel_hi:[1,0,1]
	v_pk_fma_f32 v[6:7], v[132:133], v[62:63], v[6:7] op_sel_hi:[1,0,1]
	v_pk_fma_f32 v[0:1], v[130:131], v[66:67], v[0:1] op_sel_hi:[1,0,1]
	v_pk_fma_f32 v[2:3], v[132:133], v[66:67], v[2:3] op_sel_hi:[1,0,1]
	s_waitcnt vmcnt(6)
	v_pk_fma_f32 v[16:17], v[50:51], v[134:135], v[16:17] op_sel:[1,0,0]
	v_pk_fma_f32 v[18:19], v[50:51], v[136:137], v[18:19] op_sel:[1,0,0]
	v_pk_fma_f32 v[12:13], v[134:135], v[54:55], v[12:13] op_sel:[0,1,0]
	v_pk_fma_f32 v[14:15], v[136:137], v[54:55], v[14:15] op_sel:[0,1,0]
	v_pk_fma_f32 v[8:9], v[134:135], v[58:59], v[8:9] op_sel:[0,1,0]
	v_pk_fma_f32 v[10:11], v[136:137], v[58:59], v[10:11] op_sel:[0,1,0]
	v_pk_fma_f32 v[4:5], v[134:135], v[62:63], v[4:5] op_sel:[0,1,0]
	v_pk_fma_f32 v[6:7], v[136:137], v[62:63], v[6:7] op_sel:[0,1,0]
	v_pk_fma_f32 v[0:1], v[134:135], v[66:67], v[0:1] op_sel:[0,1,0]
	v_pk_fma_f32 v[2:3], v[136:137], v[66:67], v[2:3] op_sel:[0,1,0]
	s_waitcnt vmcnt(5)
	v_pk_fma_f32 v[16:17], v[52:53], v[138:139], v[16:17] op_sel_hi:[0,1,1]
	v_pk_fma_f32 v[18:19], v[52:53], v[140:141], v[18:19] op_sel_hi:[0,1,1]
	v_pk_fma_f32 v[12:13], v[138:139], v[56:57], v[12:13] op_sel_hi:[1,0,1]
	v_pk_fma_f32 v[14:15], v[140:141], v[56:57], v[14:15] op_sel_hi:[1,0,1]
	v_pk_fma_f32 v[8:9], v[138:139], v[60:61], v[8:9] op_sel_hi:[1,0,1]
	v_pk_fma_f32 v[10:11], v[140:141], v[60:61], v[10:11] op_sel_hi:[1,0,1]
	v_pk_fma_f32 v[4:5], v[138:139], v[64:65], v[4:5] op_sel_hi:[1,0,1]
	v_pk_fma_f32 v[6:7], v[140:141], v[64:65], v[6:7] op_sel_hi:[1,0,1]
	v_pk_fma_f32 v[0:1], v[138:139], v[68:69], v[0:1] op_sel_hi:[1,0,1]
	v_pk_fma_f32 v[2:3], v[140:141], v[68:69], v[2:3] op_sel_hi:[1,0,1]
	s_waitcnt vmcnt(4)
	v_pk_fma_f32 v[16:17], v[70:71], v[142:143], v[16:17] op_sel_hi:[0,1,1]
	v_pk_fma_f32 v[18:19], v[70:71], v[144:145], v[18:19] op_sel_hi:[0,1,1]
	v_pk_fma_f32 v[12:13], v[142:143], v[72:73], v[12:13] op_sel_hi:[1,0,1]
	v_pk_fma_f32 v[14:15], v[144:145], v[72:73], v[14:15] op_sel_hi:[1,0,1]
	v_pk_fma_f32 v[8:9], v[142:143], v[74:75], v[8:9] op_sel_hi:[1,0,1]
	v_pk_fma_f32 v[10:11], v[144:145], v[74:75], v[10:11] op_sel_hi:[1,0,1]
	v_pk_fma_f32 v[4:5], v[142:143], v[76:77], v[4:5] op_sel_hi:[1,0,1]
	v_pk_fma_f32 v[6:7], v[144:145], v[76:77], v[6:7] op_sel_hi:[1,0,1]
	v_pk_fma_f32 v[0:1], v[142:143], v[78:79], v[0:1] op_sel_hi:[1,0,1]
	v_pk_fma_f32 v[2:3], v[144:145], v[78:79], v[2:3] op_sel_hi:[1,0,1]
	s_cmp_eq_u32 s6, 0x318000
	s_cbranch_scc0 .LBB0_34
	s_waitcnt vmcnt(0)
	s_barrier
	ds_write_b128 v31, v[16:19] offset:20480
	ds_write_b128 v31, v[12:15] offset:20992
	ds_write_b128 v31, v[8:11] offset:21504
	ds_write_b128 v31, v[4:7] offset:22016
	ds_write_b128 v31, v[0:3] offset:22528
	s_waitcnt lgkmcnt(0)
	s_barrier
	s_and_saveexec_b64 s[6:7], vcc
	s_cbranch_execz .LBB0_32
	s_mul_i32 s4, s8, 0x1800
	s_add_i32 s4, s4, s2
	v_or_b32_e32 v0, s4, v21
	s_mul_hi_i32 s9, s8, 5
	s_mul_i32 s8, s8, 5
	v_ashrrev_i32_e32 v1, 31, v0
	v_lshl_add_u64 v[2:3], s[2:3], 2, v[24:25]
	s_mov_b64 s[2:3], 0
	v_mov_b32_e32 v4, v20
